# filter items and ssd1 item preamble: LDS-reuse barrier moved below the load issue (down to the first LDS write)
# baseline (speedup 1.0000x reference)
.LBB0_166:
	s_and_b32 s4, s8, 7
	v_lshl_or_b32 v159, s4, 2, v145
	s_ashr_i32 s0, s8, 3
	v_or_b32_e32 v2, v159, v142
	v_readlane_b32 s16, v251, 2
	s_mul_hi_i32 s1, s0, 0x7e07e07f
	v_ashrrev_i32_e32 v3, 31, v2
	v_readlane_b32 s18, v251, 4
	v_readlane_b32 s19, v251, 5
	s_lshr_b32 s2, s1, 31
	s_ashr_i32 s1, s1, 5
	v_lshl_add_u64 v[2:3], v[2:3], 2, s[18:19]
	s_add_i32 s1, s1, s2
	global_load_dword v10, v[2:3], off
	s_mulk_i32 s1, 0x41
	s_sub_i32 s0, s0, s1
	s_mul_hi_i32 s1, s8, 0x7e07e07f
	s_lshr_b32 s2, s1, 31
	s_ashr_i32 s9, s1, 8
	s_add_i32 s9, s9, s2
	s_ashr_i32 s1, s0, 31
	s_mul_i32 s6, s9, 0x4100
	s_lshl_b64 s[2:3], s[0:1], 8
	s_mul_hi_i32 s5, s9, 0x4100
	s_add_u32 s1, s2, s6
	s_addc_u32 s10, s3, s5
	v_lshlrev_b32_e32 v0, 2, v159
	v_mov_b32_e32 v5, s10
	v_or_b32_e32 v4, s1, v144
	v_mov_b32_e32 v7, s10
	v_or_b32_e32 v6, s1, v152
	v_lshl_add_u64 v[2:3], v[146:147], 0, v[0:1]
	v_lshlrev_b64 v[4:5], 8, v[4:5]
	v_lshlrev_b64 v[6:7], 8, v[6:7]
	v_lshl_add_u64 v[4:5], v[2:3], 0, v[4:5]
	v_lshl_add_u64 v[6:7], v[2:3], 0, v[6:7]
	global_load_dword v4, v[4:5], off
	s_nop 0
	global_load_dword v5, v[6:7], off
	v_mov_b32_e32 v7, s10
	v_or_b32_e32 v6, s1, v154
	v_lshlrev_b64 v[6:7], 8, v[6:7]
	v_mov_b32_e32 v9, s10
	v_or_b32_e32 v8, s1, v156
	v_lshl_add_u64 v[6:7], v[2:3], 0, v[6:7]
	v_lshlrev_b64 v[8:9], 8, v[8:9]
	v_lshl_add_u64 v[2:3], v[2:3], 0, v[8:9]
	global_load_dword v6, v[6:7], off
	s_nop 0
	global_load_dword v7, v[2:3], off
	s_mov_b32 s2, 0x3fb8aa3b
	v_readlane_b32 s17, v251, 3
	v_readlane_b32 s20, v251, 6
	v_readlane_b32 s21, v251, 7
	v_readlane_b32 s22, v251, 8
	v_readlane_b32 s23, v251, 9
	v_readlane_b32 s24, v251, 10
	v_readlane_b32 s25, v251, 11
	v_readlane_b32 s26, v251, 12
	v_readlane_b32 s27, v251, 13
	v_readlane_b32 s28, v251, 14
	v_readlane_b32 s29, v251, 15
	v_readlane_b32 s30, v251, 16
	v_readlane_b32 s31, v251, 17
	s_waitcnt vmcnt(4)
	v_mul_f32_e32 v0, 0x3fb8aa3b, v10
	v_fma_f32 v2, v10, s2, -v0
	v_rndne_f32_e32 v3, v0
	v_fmac_f32_e32 v2, 0x32a5705f, v10
	v_sub_f32_e32 v0, v0, v3
	v_add_f32_e32 v0, v0, v2
	v_cvt_i32_f32_e32 v3, v3
	v_exp_f32_e32 v0, v0
	s_mov_b32 s2, 0xc2ce8ed0
	v_cmp_ngt_f32_e32 vcc, s2, v10
	s_mov_b32 s2, 0x42b17218
	v_ldexp_f32 v0, v0, v3
	v_cndmask_b32_e32 v0, 0, v0, vcc
	v_cmp_nlt_f32_e32 vcc, s2, v10
	v_readlane_b32 s2, v254, 9
	v_readlane_b32 s3, v254, 10
	v_cndmask_b32_e32 v2, v219, v0, vcc
	s_waitcnt vmcnt(2)
	v_pk_mul_f32 v[8:9], v[4:5], v[2:3] op_sel_hi:[1,0] neg_lo:[0,1] neg_hi:[0,1]
	s_nop 0
	v_add_f32_e32 v3, v8, v9
	s_waitcnt vmcnt(1)
	v_fma_f32 v10, -v6, v2, v3
	s_waitcnt vmcnt(0)
	v_fma_f32 v11, -v7, v2, v10
	ds_bpermute_b32 v0, v143, v11
	s_waitcnt lgkmcnt(0)
	v_add_f32_e32 v0, v11, v0
	v_cndmask_b32_e64 v0, v0, v11, s[2:3]
	ds_bpermute_b32 v12, v149, v0
	v_readlane_b32 s2, v254, 11
	v_readlane_b32 s3, v254, 12
	s_waitcnt lgkmcnt(0)
	v_add_f32_e32 v12, v0, v12
	v_cndmask_b32_e64 v0, v12, v0, s[2:3]
	ds_bpermute_b32 v12, v153, v0
	v_readlane_b32 s2, v254, 13
	v_readlane_b32 s3, v254, 14
	s_waitcnt lgkmcnt(0)
	v_add_f32_e32 v12, v0, v12
	v_cndmask_b32_e64 v0, v12, v0, s[2:3]
	ds_bpermute_b32 v12, v155, v0
	v_readlane_b32 s2, v254, 15
	v_readlane_b32 s3, v254, 16
	s_waitcnt lgkmcnt(0)
	v_add_f32_e32 v12, v0, v12
	v_cndmask_b32_e64 v0, v12, v0, s[2:3]
	ds_bpermute_b32 v12, v157, v0
	v_readlane_b32 s2, v254, 17
	v_readlane_b32 s3, v254, 18
	s_waitcnt lgkmcnt(0)
	v_add_f32_e32 v12, v0, v12
	v_cndmask_b32_e64 v0, v12, v0, s[2:3]
	ds_bpermute_b32 v12, v160, v0
	v_readlane_b32 s2, v254, 19
	v_readlane_b32 s3, v254, 20
	s_waitcnt lgkmcnt(0)
	v_add_f32_e32 v12, v0, v12
	v_cndmask_b32_e64 v0, v12, v0, s[2:3]
	v_sub_f32_e32 v12, v0, v11
	ds_bpermute_b32 v0, v161, v0
	v_add_f32_e32 v13, v8, v12
	v_add_f32_e32 v3, v3, v12
	v_add_f32_e32 v10, v10, v12
	v_add_f32_e32 v11, v11, v12
	v_sub_f32_e32 v8, v13, v8
	v_sub_f32_e32 v9, v3, v9
	s_waitcnt lgkmcnt(0)
	v_sub_f32_e32 v12, v0, v13
	v_sub_f32_e32 v3, v0, v3
	v_sub_f32_e32 v13, v0, v10
	v_fmac_f32_e32 v10, v6, v2
	v_sub_f32_e32 v14, v0, v11
	v_fmac_f32_e32 v11, v7, v2
	v_cndmask_b32_e64 v2, v8, v12, s[52:53]
	v_cndmask_b32_e64 v3, v9, v3, s[52:53]
	v_cndmask_b32_e64 v8, v10, v13, s[52:53]
	v_cndmask_b32_e64 v9, v11, v14, s[52:53]
	v_mul_f32_e32 v2, 0x3fb8aa3b, v2
	v_mul_f32_e32 v3, 0x3fb8aa3b, v3
	v_mul_f32_e32 v8, 0x3fb8aa3b, v8
	v_mul_f32_e32 v9, 0x3fb8aa3b, v9
	v_exp_f32_e32 v2, v2
	v_exp_f32_e32 v3, v3
	v_exp_f32_e32 v8, v8
	v_exp_f32_e32 v9, v9
	v_pk_mul_f32 v[2:3], v[4:5], v[2:3]
	v_pk_mul_f32 v[4:5], v[6:7], v[8:9]
	s_barrier
	ds_write_b128 v187, v[2:5]
	s_and_saveexec_b64 s[2:3], s[54:55]
	s_cbranch_execz .LBB0_168
	v_add_u32_e32 v2, s9, v162
	v_mul_f32_e32 v0, 0x3fb8aa3b, v0
	v_lshl_add_u32 v2, v2, 6, v2
	v_exp_f32_e32 v0, v0
	v_add_u32_e32 v2, s0, v2
	v_lshl_or_b32 v2, v2, 5, v159
	v_readlane_b32 s6, v251, 34
	v_ashrrev_i32_e32 v3, 31, v2
	v_readlane_b32 s7, v251, 35
	s_nop 1
	v_lshl_add_u64 v[2:3], v[2:3], 2, s[6:7]
	global_store_dword v[2:3], v0, off

.LBB0_1326:
	s_movk_i32 s12, 0x104
	s_movk_i32 s13, 0x5ff
	s_lshl_b32 s4, s4, 2
	v_readlane_b32 s6, v252, 8
	v_readlane_b32 s7, v252, 9
	s_add_u32 s4, s6, s4
	s_addc_u32 s5, s7, 0
	s_lshl_b32 s11, s10, 7
	v_mov_b32_e32 v111, v1
	v_add_u32_e32 v112, 0x0, v42
	v_ashrrev_i32_e32 v113, 4, v112
	v_add_u32_e32 v108, s11, v113
	v_ashrrev_i32_e32 v109, 31, v108
	v_lshlrev_b64 v[108:109], 8, v[108:109]
	v_add_u32_e32 v110, 0x0, v46
	v_lshlrev_b32_e32 v110, 2, v110
	v_lshl_add_u64 v[108:109], s[4:5], 0, v[108:109]
	v_and_b32_e32 v110, 0xf0, v110
	v_lshl_add_u64 v[108:109], v[108:109], 0, v[110:111]
	v_mul_lo_u32 v84, v113, s12
	v_add3_u32 v84, 32, v84, v110
	global_load_dwordx4 v[68:71], v[108:109], off
	v_add_u32_e32 v112, 0x200, v42
	v_ashrrev_i32_e32 v113, 4, v112
	v_add_u32_e32 v108, s11, v113
	v_ashrrev_i32_e32 v109, 31, v108
	v_lshlrev_b64 v[108:109], 8, v[108:109]
	v_add_u32_e32 v110, 0x800, v46
	v_lshlrev_b32_e32 v110, 2, v110
	v_lshl_add_u64 v[108:109], s[4:5], 0, v[108:109]
	v_and_b32_e32 v110, 0xf0, v110
	v_lshl_add_u64 v[108:109], v[108:109], 0, v[110:111]
	v_mul_lo_u32 v85, v113, s12
	v_add3_u32 v85, 32, v85, v110
	global_load_dwordx4 v[72:75], v[108:109], off
	v_add_u32_e32 v112, 0x400, v42
	v_ashrrev_i32_e32 v113, 4, v112
	v_add_u32_e32 v108, s11, v113
	v_ashrrev_i32_e32 v109, 31, v108
	v_lshlrev_b64 v[108:109], 8, v[108:109]
	v_add_u32_e32 v110, 0x1000, v46
	v_lshlrev_b32_e32 v110, 2, v110
	v_lshl_add_u64 v[108:109], s[4:5], 0, v[108:109]
	v_and_b32_e32 v110, 0xf0, v110
	v_lshl_add_u64 v[108:109], v[108:109], 0, v[110:111]
	v_mul_lo_u32 v86, v113, s12
	v_add3_u32 v86, 32, v86, v110
	global_load_dwordx4 v[76:79], v[108:109], off
	v_add_u32_e32 v112, 0x600, v42
	v_ashrrev_i32_e32 v113, 4, v112
	v_add_u32_e32 v108, s11, v113
	v_ashrrev_i32_e32 v109, 31, v108
	v_lshlrev_b64 v[108:109], 8, v[108:109]
	v_add_u32_e32 v110, 0x1800, v46
	v_lshlrev_b32_e32 v110, 2, v110
	v_lshl_add_u64 v[108:109], s[4:5], 0, v[108:109]
	v_and_b32_e32 v110, 0xf0, v110
	v_lshl_add_u64 v[108:109], v[108:109], 0, v[110:111]
	v_mul_lo_u32 v87, v113, s12
	v_add3_u32 v87, 32, v87, v110
	global_load_dwordx4 v[80:83], v[108:109], off
	s_lshl_b32 s2, s8, 7
	s_and_b32 s11, s2, 0x780
	s_movk_i32 s12, 0x5ff
	v_readlane_b32 s16, v254, 23
	s_lshl_b32 s4, s11, 2
	v_readlane_b32 s30, v254, 37
	v_readlane_b32 s31, v254, 38
	s_add_u32 s4, s30, s4
	s_addc_u32 s5, s31, 0
	v_readlane_b32 s17, v254, 24
	v_readlane_b32 s18, v254, 25
	v_readlane_b32 s19, v254, 26
	v_readlane_b32 s20, v254, 27
	v_readlane_b32 s21, v254, 28
	v_readlane_b32 s22, v254, 29
	v_readlane_b32 s23, v254, 30
	v_readlane_b32 s24, v254, 31
	v_readlane_b32 s25, v254, 32
	v_readlane_b32 s26, v254, 33
	v_readlane_b32 s27, v254, 34
	v_readlane_b32 s28, v254, 35
	v_readlane_b32 s29, v254, 36
	v_add_u32_e32 v112, 0x0, v42
	v_ashrrev_i32_e32 v113, 5, v112
	v_ashrrev_i32_e32 v109, 31, v113
	v_mov_b32_e32 v108, v113
	v_lshlrev_b64 v[108:109], 13, v[108:109]
	v_add_u32_e32 v110, 0x0, v46
	v_lshlrev_b32_e32 v110, 2, v110
	v_lshl_add_u64 v[108:109], s[4:5], 0, v[108:109]
	v_and_b32_e32 v110, 0x1f0, v110
	v_lshl_add_u64 v[108:109], v[108:109], 0, v[110:111]
	v_lshlrev_b32_e32 v104, 9, v113
	v_add3_u32 v104, 32, v104, v110
	global_load_dwordx4 v[88:91], v[108:109], off
	v_add_u32_e32 v112, 0x200, v42
	v_ashrrev_i32_e32 v113, 5, v112
	v_ashrrev_i32_e32 v109, 31, v113
	v_mov_b32_e32 v108, v113
	v_lshlrev_b64 v[108:109], 13, v[108:109]
	v_add_u32_e32 v110, 0x800, v46
	v_lshlrev_b32_e32 v110, 2, v110
	v_lshl_add_u64 v[108:109], s[4:5], 0, v[108:109]
	v_and_b32_e32 v110, 0x1f0, v110
	v_lshl_add_u64 v[108:109], v[108:109], 0, v[110:111]
	v_lshlrev_b32_e32 v105, 9, v113
	v_add3_u32 v105, 32, v105, v110
	global_load_dwordx4 v[92:95], v[108:109], off
	v_add_u32_e32 v112, 0x400, v42
	v_ashrrev_i32_e32 v113, 5, v112
	v_ashrrev_i32_e32 v109, 31, v113
	v_mov_b32_e32 v108, v113
	v_lshlrev_b64 v[108:109], 13, v[108:109]
	v_add_u32_e32 v110, 0x1000, v46
	v_lshlrev_b32_e32 v110, 2, v110
	v_lshl_add_u64 v[108:109], s[4:5], 0, v[108:109]
	v_and_b32_e32 v110, 0x1f0, v110
	v_lshl_add_u64 v[108:109], v[108:109], 0, v[110:111]
	v_lshlrev_b32_e32 v106, 9, v113
	v_add3_u32 v106, 32, v106, v110
	global_load_dwordx4 v[96:99], v[108:109], off
	v_add_u32_e32 v112, 0x600, v42
	v_ashrrev_i32_e32 v113, 5, v112
	v_ashrrev_i32_e32 v109, 31, v113
	v_mov_b32_e32 v108, v113
	v_lshlrev_b64 v[108:109], 13, v[108:109]
	v_add_u32_e32 v110, 0x1800, v46
	v_lshlrev_b32_e32 v110, 2, v110
	v_lshl_add_u64 v[108:109], s[4:5], 0, v[108:109]
	v_and_b32_e32 v110, 0x1f0, v110
	v_lshl_add_u64 v[108:109], v[108:109], 0, v[110:111]
	v_lshlrev_b32_e32 v107, 9, v113
	v_add3_u32 v107, 32, v107, v110
	global_load_dwordx4 v[100:103], v[108:109], off
	v_and_b32_e32 v156, 31, v42
	v_bfe_u32 v157, v42, 5, 1
	v_lshrrev_b32_e32 v108, 8, v42
	v_bfe_u32 v109, v42, 6, 2
	v_lshl_add_u32 v158, v108, 6, v156
	v_lshlrev_b32_e32 v158, 2, v158
	v_lshl_add_u32 v158, v157, 9, v158
	v_add_u32_e32 v158, 0x8220, v158
	v_lshl_add_u32 v159, v109, 5, v156
	v_mul_u32_u24_e32 v159, 0x104, v159
	v_lshl_add_u32 v159, v157, 2, v159
	v_add_u32_e32 v159, 32, v159
	v_lshlrev_b32_e32 v112, 4, v157
	v_lshl_add_u32 v112, v108, 8, v112
	v_readlane_b32 s12, v254, 39
	v_readlane_b32 s13, v254, 40
	s_lshl_b32 s2, s11, 2
	s_add_u32 s12, s12, s2
	s_addc_u32 s13, s13, 0
	global_load_dwordx4 v[124:127], v112, s[12:13]
	global_load_dwordx4 v[128:131], v112, s[12:13] offset:32
	global_load_dwordx4 v[132:135], v112, s[12:13] offset:64
	global_load_dwordx4 v[136:139], v112, s[12:13] offset:96
	global_load_dwordx4 v[140:143], v112, s[12:13] offset:128
	global_load_dwordx4 v[144:147], v112, s[12:13] offset:160
	global_load_dwordx4 v[148:151], v112, s[12:13] offset:192
	global_load_dwordx4 v[152:155], v112, s[12:13] offset:224
	s_waitcnt lgkmcnt(0)
	s_barrier
	s_waitcnt vmcnt(15)
	ds_write2_b32 v84, v68, v69 offset1:1
	ds_write2_b32 v84, v70, v71 offset0:2 offset1:3
	s_waitcnt vmcnt(14)
	ds_write2_b32 v85, v72, v73 offset1:1
	ds_write2_b32 v85, v74, v75 offset0:2 offset1:3
	s_waitcnt vmcnt(13)
	ds_write2_b32 v86, v76, v77 offset1:1
	ds_write2_b32 v86, v78, v79 offset0:2 offset1:3
	s_waitcnt vmcnt(12)
	ds_write2_b32 v87, v80, v81 offset1:1
	ds_write2_b32 v87, v82, v83 offset0:2 offset1:3
	s_waitcnt vmcnt(11)
	ds_write_b128 v104, v[88:91] offset:33280
	s_waitcnt vmcnt(10)
	ds_write_b128 v105, v[92:95] offset:33280
	s_waitcnt vmcnt(9)
	ds_write_b128 v106, v[96:99] offset:33280
	s_waitcnt vmcnt(8)
	ds_write_b128 v107, v[100:103] offset:33280
